# v012 + attention / cross-attention / gMLP epilogues store dwordx4 rows built with v_permlane32_swap instead of dwordx2 pieces
# speedup vs baseline: 1.0052x; 1.0035x over previous
; template <bool DIFF>
; __device__ __forceinline__ void attn_unit(LAS unsigned char* lds, const bf16_t* Qp, int ldq, const bf16_t* Kp, const bf16_t* Vp, int ldkv,
;                                           bf16_t* Op, int qb, float lam, const float* subln, const float sbound, const int tid) {
;     ...
;         __syncthreads();
;         if (c == 0) {
;             float ss = 0.f;
; #pragma unroll
;             for (int d = 0; d < NDV; ++d)
; #pragma unroll
;                 for (int i = 0; i < 16; ++i) { const float v = o[d][i] * inv - ex[(d * 16 + i) * 64]; o[d][i] = v; ss += v * v; }
.LBB0_61:
	s_andn2_b64 vcc, exec, s[10:11]
	s_waitcnt lgkmcnt(0)
	s_barrier
	s_cbranch_vccnz .LBB0_40
	ds_read2st64_b32 v[156:157], v0 offset1:1
	ds_read2st64_b32 v[158:159], v0 offset0:2 offset1:3
	ds_read2st64_b32 v[160:161], v0 offset0:4 offset1:5
	ds_read2st64_b32 v[162:163], v0 offset0:6 offset1:7
	ds_read2st64_b32 v[164:165], v0 offset0:8 offset1:9
	ds_read2st64_b32 v[166:167], v0 offset0:10 offset1:11
	ds_read2st64_b32 v[168:169], v0 offset0:12 offset1:13
	ds_read2st64_b32 v[170:171], v0 offset0:14 offset1:15
	ds_read2st64_b32 v[172:173], v0 offset0:16 offset1:17
	ds_read2st64_b32 v[174:175], v0 offset0:18 offset1:19
	ds_read2st64_b32 v[176:177], v0 offset0:20 offset1:21
	ds_read2st64_b32 v[178:179], v0 offset0:22 offset1:23
	ds_read2st64_b32 v[204:205], v0 offset0:24 offset1:25
	ds_read2st64_b32 v[206:207], v0 offset0:26 offset1:27
	ds_read2st64_b32 v[230:231], v0 offset0:28 offset1:29
	ds_read2st64_b32 v[232:233], v0 offset0:30 offset1:31
	ds_read2st64_b32 v[234:235], v0 offset0:32 offset1:33
	ds_read2st64_b32 v[236:237], v0 offset0:34 offset1:35
	ds_read2st64_b32 v[238:239], v0 offset0:36 offset1:37
	ds_read2st64_b32 v[240:241], v0 offset0:38 offset1:39
	ds_read2st64_b32 v[152:153], v0 offset0:40 offset1:41
	ds_read2st64_b32 v[154:155], v0 offset0:42 offset1:43
	ds_read2st64_b32 v[148:149], v0 offset0:44 offset1:45
	ds_read2st64_b32 v[150:151], v0 offset0:46 offset1:47
	ds_read2st64_b32 v[144:145], v0 offset0:48 offset1:49
	ds_read2st64_b32 v[146:147], v0 offset0:50 offset1:51
	ds_read2st64_b32 v[140:141], v0 offset0:52 offset1:53
	ds_read2st64_b32 v[142:143], v0 offset0:54 offset1:55
	ds_read2st64_b32 v[136:137], v0 offset0:56 offset1:57
	ds_read2st64_b32 v[138:139], v0 offset0:58 offset1:59
	ds_read2st64_b32 v[132:133], v0 offset0:60 offset1:61
	ds_read2st64_b32 v[134:135], v0 offset0:62 offset1:63
	s_waitcnt lgkmcnt(14)
	v_pk_fma_f32 v[64:65], v[64:65], v[14:15], v[156:157] op_sel_hi:[1,0,1] neg_lo:[0,0,1] neg_hi:[0,0,1]
	v_pk_fma_f32 v[66:67], v[66:67], v[14:15], v[158:159] op_sel_hi:[1,0,1] neg_lo:[0,0,1] neg_hi:[0,0,1]
	v_mul_f32_e32 v156, v65, v65
	v_pk_fma_f32 v[156:157], v[64:65], v[64:65], v[156:157] op_sel_hi:[1,1,0]
	v_mul_f32_e32 v158, v67, v67
	v_pk_fma_f32 v[156:157], v[66:67], v[66:67], v[156:157]
	v_pk_fma_f32 v[68:69], v[68:69], v[14:15], v[160:161] op_sel_hi:[1,0,1] neg_lo:[0,0,1] neg_hi:[0,0,1]
	v_pk_add_f32 v[156:157], v[156:157], v[158:159] op_sel_hi:[1,0]
	v_mul_f32_e32 v158, v69, v69
	v_pk_fma_f32 v[156:157], v[68:69], v[68:69], v[156:157]
	v_pk_fma_f32 v[70:71], v[70:71], v[14:15], v[162:163] op_sel_hi:[1,0,1] neg_lo:[0,0,1] neg_hi:[0,0,1]
	v_pk_add_f32 v[156:157], v[156:157], v[158:159] op_sel_hi:[1,0]
	v_mul_f32_e32 v158, v71, v71
	v_pk_fma_f32 v[156:157], v[70:71], v[70:71], v[156:157]
	v_pk_fma_f32 v[72:73], v[72:73], v[14:15], v[164:165] op_sel_hi:[1,0,1] neg_lo:[0,0,1] neg_hi:[0,0,1]
	v_pk_add_f32 v[156:157], v[156:157], v[158:159] op_sel_hi:[1,0]
	v_mul_f32_e32 v158, v73, v73
	v_pk_fma_f32 v[156:157], v[72:73], v[72:73], v[156:157]
	v_pk_fma_f32 v[74:75], v[74:75], v[14:15], v[166:167] op_sel_hi:[1,0,1] neg_lo:[0,0,1] neg_hi:[0,0,1]
	v_pk_add_f32 v[156:157], v[156:157], v[158:159] op_sel_hi:[1,0]
	v_mul_f32_e32 v158, v75, v75
	v_pk_fma_f32 v[156:157], v[74:75], v[74:75], v[156:157]
	v_pk_fma_f32 v[76:77], v[76:77], v[14:15], v[168:169] op_sel_hi:[1,0,1] neg_lo:[0,0,1] neg_hi:[0,0,1]
	v_pk_add_f32 v[156:157], v[156:157], v[158:159] op_sel_hi:[1,0]
	v_mul_f32_e32 v158, v77, v77
	v_pk_fma_f32 v[156:157], v[76:77], v[76:77], v[156:157]
	v_pk_fma_f32 v[78:79], v[78:79], v[14:15], v[170:171] op_sel_hi:[1,0,1] neg_lo:[0,0,1] neg_hi:[0,0,1]
	v_pk_add_f32 v[156:157], v[156:157], v[158:159] op_sel_hi:[1,0]
	v_mul_f32_e32 v158, v79, v79
	v_pk_fma_f32 v[156:157], v[78:79], v[78:79], v[156:157]
	v_pk_fma_f32 v[48:49], v[48:49], v[14:15], v[172:173] op_sel_hi:[1,0,1] neg_lo:[0,0,1] neg_hi:[0,0,1]
	v_pk_add_f32 v[156:157], v[156:157], v[158:159] op_sel_hi:[1,0]
	v_mul_f32_e32 v158, v49, v49
	v_pk_fma_f32 v[156:157], v[48:49], v[48:49], v[156:157]
	v_pk_fma_f32 v[50:51], v[50:51], v[14:15], v[174:175] op_sel_hi:[1,0,1] neg_lo:[0,0,1] neg_hi:[0,0,1]
	v_pk_add_f32 v[156:157], v[156:157], v[158:159] op_sel_hi:[1,0]
	v_mul_f32_e32 v158, v51, v51
	v_pk_fma_f32 v[156:157], v[50:51], v[50:51], v[156:157]
	v_pk_fma_f32 v[52:53], v[52:53], v[14:15], v[176:177] op_sel_hi:[1,0,1] neg_lo:[0,0,1] neg_hi:[0,0,1]
	v_pk_add_f32 v[156:157], v[156:157], v[158:159] op_sel_hi:[1,0]
	v_mul_f32_e32 v158, v53, v53
	v_pk_fma_f32 v[156:157], v[52:53], v[52:53], v[156:157]
	v_pk_fma_f32 v[54:55], v[54:55], v[14:15], v[178:179] op_sel_hi:[1,0,1] neg_lo:[0,0,1] neg_hi:[0,0,1]
	v_pk_add_f32 v[156:157], v[156:157], v[158:159] op_sel_hi:[1,0]
	v_mul_f32_e32 v158, v55, v55
	v_pk_fma_f32 v[156:157], v[54:55], v[54:55], v[156:157]
	v_pk_fma_f32 v[56:57], v[56:57], v[14:15], v[204:205] op_sel_hi:[1,0,1] neg_lo:[0,0,1] neg_hi:[0,0,1]
	v_pk_add_f32 v[156:157], v[156:157], v[158:159] op_sel_hi:[1,0]
	v_mul_f32_e32 v158, v57, v57
	v_pk_fma_f32 v[156:157], v[56:57], v[56:57], v[156:157]
	v_pk_fma_f32 v[58:59], v[58:59], v[14:15], v[206:207] op_sel_hi:[1,0,1] neg_lo:[0,0,1] neg_hi:[0,0,1]
	v_pk_add_f32 v[156:157], v[156:157], v[158:159] op_sel_hi:[1,0]
	v_mul_f32_e32 v158, v59, v59
	v_pk_fma_f32 v[156:157], v[58:59], v[58:59], v[156:157]
	v_pk_fma_f32 v[60:61], v[60:61], v[14:15], v[230:231] op_sel_hi:[1,0,1] neg_lo:[0,0,1] neg_hi:[0,0,1]
	v_pk_add_f32 v[156:157], v[156:157], v[158:159] op_sel_hi:[1,0]
	v_mul_f32_e32 v158, v61, v61
	v_pk_fma_f32 v[156:157], v[60:61], v[60:61], v[156:157]
	v_pk_fma_f32 v[62:63], v[62:63], v[14:15], v[232:233] op_sel_hi:[1,0,1] neg_lo:[0,0,1] neg_hi:[0,0,1]
	v_pk_add_f32 v[156:157], v[156:157], v[158:159] op_sel_hi:[1,0]
	v_mul_f32_e32 v158, v63, v63
	v_pk_fma_f32 v[156:157], v[62:63], v[62:63], v[156:157]
	v_pk_fma_f32 v[32:33], v[32:33], v[14:15], v[234:235] op_sel_hi:[1,0,1] neg_lo:[0,0,1] neg_hi:[0,0,1]
	v_pk_add_f32 v[156:157], v[156:157], v[158:159] op_sel_hi:[1,0]
	v_mul_f32_e32 v158, v33, v33
	v_pk_fma_f32 v[156:157], v[32:33], v[32:33], v[156:157]
	v_pk_fma_f32 v[34:35], v[34:35], v[14:15], v[236:237] op_sel_hi:[1,0,1] neg_lo:[0,0,1] neg_hi:[0,0,1]
	v_pk_add_f32 v[156:157], v[156:157], v[158:159] op_sel_hi:[1,0]
	v_mul_f32_e32 v158, v35, v35
	v_pk_fma_f32 v[156:157], v[34:35], v[34:35], v[156:157]
	s_waitcnt lgkmcnt(13)
; template <bool DIFF>
; __device__ __forceinline__ void attn_unit(LAS unsigned char* lds, const bf16_t* Qp, int ldq, const bf16_t* Kp, const bf16_t* Vp, int ldkv,
;                                           bf16_t* Op, int qb, float lam, const float* subln, const float sbound, const int tid) {
;     ...
;             float ss = 0.f;
; #pragma unroll
;             for (int d = 0; d < NDV; ++d)
; #pragma unroll
;                 for (int i = 0; i < 16; ++i) { const float v = o[d][i] * inv - ex[(d * 16 + i) * 64]; o[d][i] = v; ss += v * v; }
	v_pk_fma_f32 v[36:37], v[36:37], v[14:15], v[238:239] op_sel_hi:[1,0,1] neg_lo:[0,0,1] neg_hi:[0,0,1]
	v_pk_add_f32 v[156:157], v[156:157], v[158:159] op_sel_hi:[1,0]
	v_mul_f32_e32 v158, v37, v37
	v_pk_fma_f32 v[156:157], v[36:37], v[36:37], v[156:157]
	s_waitcnt lgkmcnt(12)
	v_pk_fma_f32 v[38:39], v[38:39], v[14:15], v[240:241] op_sel_hi:[1,0,1] neg_lo:[0,0,1] neg_hi:[0,0,1]
	v_pk_add_f32 v[156:157], v[156:157], v[158:159] op_sel_hi:[1,0]
	v_mul_f32_e32 v158, v39, v39
	v_pk_fma_f32 v[156:157], v[38:39], v[38:39], v[156:157]
	s_waitcnt lgkmcnt(11)
	v_pk_fma_f32 v[40:41], v[40:41], v[14:15], v[152:153] op_sel_hi:[1,0,1] neg_lo:[0,0,1] neg_hi:[0,0,1]
	v_pk_add_f32 v[156:157], v[156:157], v[158:159] op_sel_hi:[1,0]
	s_waitcnt lgkmcnt(10)
	v_pk_fma_f32 v[42:43], v[42:43], v[14:15], v[154:155] op_sel_hi:[1,0,1] neg_lo:[0,0,1] neg_hi:[0,0,1]
	v_pk_fma_f32 v[152:153], v[40:41], v[40:41], v[156:157]
	v_mul_f32_e32 v154, v41, v41
	v_pk_add_f32 v[152:153], v[152:153], v[154:155] op_sel_hi:[1,0]
	v_mul_f32_e32 v154, v43, v43
	v_pk_fma_f32 v[152:153], v[42:43], v[42:43], v[152:153]
	s_waitcnt lgkmcnt(9)
	v_pk_fma_f32 v[44:45], v[44:45], v[14:15], v[148:149] op_sel_hi:[1,0,1] neg_lo:[0,0,1] neg_hi:[0,0,1]
	v_pk_add_f32 v[152:153], v[152:153], v[154:155] op_sel_hi:[1,0]
	s_waitcnt lgkmcnt(8)
	v_pk_fma_f32 v[46:47], v[46:47], v[14:15], v[150:151] op_sel_hi:[1,0,1] neg_lo:[0,0,1] neg_hi:[0,0,1]
	v_pk_fma_f32 v[148:149], v[44:45], v[44:45], v[152:153]
	v_mul_f32_e32 v150, v45, v45
	v_pk_add_f32 v[148:149], v[148:149], v[150:151] op_sel_hi:[1,0]
	v_mul_f32_e32 v150, v47, v47
	v_pk_fma_f32 v[148:149], v[46:47], v[46:47], v[148:149]
	s_waitcnt lgkmcnt(7)
	v_pk_fma_f32 v[16:17], v[16:17], v[14:15], v[144:145] op_sel_hi:[1,0,1] neg_lo:[0,0,1] neg_hi:[0,0,1]
	v_pk_add_f32 v[148:149], v[148:149], v[150:151] op_sel_hi:[1,0]
	s_waitcnt lgkmcnt(6)
	v_pk_fma_f32 v[18:19], v[18:19], v[14:15], v[146:147] op_sel_hi:[1,0,1] neg_lo:[0,0,1] neg_hi:[0,0,1]
	v_pk_fma_f32 v[144:145], v[16:17], v[16:17], v[148:149]
	v_mul_f32_e32 v146, v17, v17
	v_pk_add_f32 v[144:145], v[144:145], v[146:147] op_sel_hi:[1,0]
	v_mul_f32_e32 v146, v19, v19
	v_pk_fma_f32 v[144:145], v[18:19], v[18:19], v[144:145]
	s_waitcnt lgkmcnt(5)
	v_pk_fma_f32 v[20:21], v[20:21], v[14:15], v[140:141] op_sel_hi:[1,0,1] neg_lo:[0,0,1] neg_hi:[0,0,1]
	v_pk_add_f32 v[144:145], v[144:145], v[146:147] op_sel_hi:[1,0]
	s_waitcnt lgkmcnt(4)
	v_pk_fma_f32 v[22:23], v[22:23], v[14:15], v[142:143] op_sel_hi:[1,0,1] neg_lo:[0,0,1] neg_hi:[0,0,1]
	v_pk_fma_f32 v[140:141], v[20:21], v[20:21], v[144:145]
	v_mul_f32_e32 v142, v21, v21
	v_pk_add_f32 v[140:141], v[140:141], v[142:143] op_sel_hi:[1,0]
	v_mul_f32_e32 v142, v23, v23
	v_pk_fma_f32 v[140:141], v[22:23], v[22:23], v[140:141]
	s_waitcnt lgkmcnt(3)
	v_pk_fma_f32 v[24:25], v[24:25], v[14:15], v[136:137] op_sel_hi:[1,0,1] neg_lo:[0,0,1] neg_hi:[0,0,1]
	v_pk_add_f32 v[140:141], v[140:141], v[142:143] op_sel_hi:[1,0]
	s_waitcnt lgkmcnt(2)
	v_pk_fma_f32 v[26:27], v[26:27], v[14:15], v[138:139] op_sel_hi:[1,0,1] neg_lo:[0,0,1] neg_hi:[0,0,1]
	v_pk_fma_f32 v[136:137], v[24:25], v[24:25], v[140:141]
	v_mul_f32_e32 v138, v25, v25
	v_pk_add_f32 v[136:137], v[136:137], v[138:139] op_sel_hi:[1,0]
	v_mul_f32_e32 v138, v27, v27
	v_pk_fma_f32 v[136:137], v[26:27], v[26:27], v[136:137]
	s_waitcnt lgkmcnt(0)
; __device__ __forceinline__ unsigned pk_bf16(float lo, float hi) { f32x2 v = {lo, hi}; bf16x2_t b = __builtin_convertvector(v, bf16x2_t); return __builtin_bit_cast(unsigned, b); }
; template <bool DIFF>
; __device__ __forceinline__ void attn_unit(LAS unsigned char* lds, const bf16_t* Qp, int ldq, const bf16_t* Kp, const bf16_t* Vp, int ldkv,
;                                           bf16_t* Op, int qb, float lam, const float* subln, const float sbound, const int tid) {
;     ...
;             ss = xor32_sum(ss);
;             const float rr = rsqrtf(ss * (1.f / 128.f) + EPS) * (1.f - LAMBDA_INIT);
;             bf16_t* orow = Op + (size_t)(sq * 32 + r) * DM + 4 * h;
; #pragma unroll
;             for (int d = 0; d < NDV; ++d)
; #pragma unroll
;                 for (int g = 0; g < 4; ++g) {
;                     const f32x4 gv = gn[d * 4 + g];
;                     u32x2 wv; wv.x = pk_bf16(o[d][4 * g] * rr * gv[0], o[d][4 * g + 1] * rr * gv[1]); wv.y = pk_bf16(o[d][4 * g + 2] * rr * gv[2], o[d][4 * g + 3] * rr * gv[3]);
;                     *(u32x2*)(orow + d * 32 + 8 * g) = wv;
;                 }
	v_pk_fma_f32 v[30:31], v[30:31], v[14:15], v[134:135] op_sel_hi:[1,0,1] neg_lo:[0,0,1] neg_hi:[0,0,1]
	v_pk_add_f32 v[136:137], v[136:137], v[138:139] op_sel_hi:[1,0]
	v_pk_fma_f32 v[14:15], v[28:29], v[14:15], v[132:133] op_sel_hi:[1,0,1] neg_lo:[0,0,1] neg_hi:[0,0,1]
	s_lshl_b64 s[6:7], s[6:7], 11
	v_pk_fma_f32 v[28:29], v[14:15], v[14:15], v[136:137]
	v_mul_f32_e32 v132, v15, v15
	v_pk_add_f32 v[28:29], v[28:29], v[132:133] op_sel_hi:[1,0]
	v_mul_f32_e32 v132, v31, v31
	v_pk_fma_f32 v[28:29], v[30:31], v[30:31], v[28:29]
	s_add_u32 s6, s12, s6
	v_pk_add_f32 v[28:29], v[28:29], v[132:133] op_sel_hi:[1,0]
	s_addc_u32 s7, s13, s7
	v_mov_b32_e32 v29, v28
	s_nop 1
	v_permlane32_swap_b32_e32 v28, v29
	v_add_f32_e32 v28, v28, v29
	v_fmamk_f32 v28, v28, 0x3c000000, v182
	v_mul_f32_e32 v29, 0x4b800000, v28
	v_cmp_gt_f32_e32 vcc, s89, v28
	s_add_u32 s6, s6, s8
	s_addc_u32 s7, s7, s9
	v_cndmask_b32_e32 v28, v28, v29, vcc
	v_rsq_f32_e32 v132, v28
	v_lshlrev_b32_e32 v0, 11, v229
	v_lshl_add_u64 v[28:29], s[6:7], 0, v[0:1]
	v_lshlrev_b32_e32 v0, 1, v198
	v_lshl_add_u64 v[28:29], v[28:29], 0, v[0:1]
	v_mul_f32_e32 v0, 0x45800000, v132
	v_cndmask_b32_e32 v0, v132, v0, vcc
	v_mul_f32_e32 v0, 0x3f24fd5c, v0
	v_and_b32_e32 v132, 32, v197
	v_lshrrev_b32_e32 v132, 2, v132
	v_add_co_u32_e32 v28, vcc, v132, v28
	s_nop 1
	v_addc_co_u32_e32 v29, vcc, 0, v29, vcc
	v_pk_mul_f32 v[64:65], v[64:65], v[0:1] op_sel_hi:[1,0]
	v_pk_mul_f32 v[66:67], v[66:67], v[0:1] op_sel_hi:[1,0]
	v_pk_mul_f32 v[64:65], v[128:129], v[64:65]
	v_pk_mul_f32 v[66:67], v[130:131], v[66:67]
	v_pk_mul_f32 v[68:69], v[68:69], v[0:1] op_sel_hi:[1,0]
	v_pk_mul_f32 v[70:71], v[70:71], v[0:1] op_sel_hi:[1,0]
	v_pk_mul_f32 v[68:69], v[124:125], v[68:69]
	v_pk_mul_f32 v[70:71], v[126:127], v[70:71]
	v_cvt_pk_bf16_f32 v64, v64, v65
	v_cvt_pk_bf16_f32 v65, v66, v67
	v_cvt_pk_bf16_f32 v66, v68, v69
	v_cvt_pk_bf16_f32 v67, v70, v71
	v_pk_mul_f32 v[72:73], v[72:73], v[0:1] op_sel_hi:[1,0]
	v_pk_mul_f32 v[74:75], v[74:75], v[0:1] op_sel_hi:[1,0]
	v_pk_mul_f32 v[72:73], v[120:121], v[72:73]
	v_pk_mul_f32 v[74:75], v[122:123], v[74:75]
	v_pk_mul_f32 v[76:77], v[76:77], v[0:1] op_sel_hi:[1,0]
	v_pk_mul_f32 v[78:79], v[78:79], v[0:1] op_sel_hi:[1,0]
	v_pk_mul_f32 v[76:77], v[116:117], v[76:77]
	v_pk_mul_f32 v[78:79], v[118:119], v[78:79]
	v_cvt_pk_bf16_f32 v72, v72, v73
	v_cvt_pk_bf16_f32 v73, v74, v75
	v_cvt_pk_bf16_f32 v74, v76, v77
	v_cvt_pk_bf16_f32 v75, v78, v79
	v_pk_mul_f32 v[48:49], v[48:49], v[0:1] op_sel_hi:[1,0]
	v_pk_mul_f32 v[50:51], v[50:51], v[0:1] op_sel_hi:[1,0]
	v_pk_mul_f32 v[48:49], v[112:113], v[48:49]
	v_pk_mul_f32 v[50:51], v[114:115], v[50:51]
	v_pk_mul_f32 v[52:53], v[52:53], v[0:1] op_sel_hi:[1,0]
	v_pk_mul_f32 v[54:55], v[54:55], v[0:1] op_sel_hi:[1,0]
	v_pk_mul_f32 v[52:53], v[108:109], v[52:53]
	v_pk_mul_f32 v[54:55], v[110:111], v[54:55]
	v_cvt_pk_bf16_f32 v48, v48, v49
	v_cvt_pk_bf16_f32 v49, v50, v51
	v_cvt_pk_bf16_f32 v50, v52, v53
	v_cvt_pk_bf16_f32 v51, v54, v55
	v_pk_mul_f32 v[56:57], v[56:57], v[0:1] op_sel_hi:[1,0]
	v_pk_mul_f32 v[58:59], v[58:59], v[0:1] op_sel_hi:[1,0]
	v_pk_mul_f32 v[56:57], v[104:105], v[56:57]
	v_pk_mul_f32 v[58:59], v[106:107], v[58:59]
	v_pk_mul_f32 v[60:61], v[60:61], v[0:1] op_sel_hi:[1,0]
	v_pk_mul_f32 v[62:63], v[62:63], v[0:1] op_sel_hi:[1,0]
	v_pk_mul_f32 v[60:61], v[100:101], v[60:61]
	v_pk_mul_f32 v[62:63], v[102:103], v[62:63]
	v_cvt_pk_bf16_f32 v56, v56, v57
	v_cvt_pk_bf16_f32 v57, v58, v59
	v_cvt_pk_bf16_f32 v58, v60, v61
	v_cvt_pk_bf16_f32 v59, v62, v63
	v_pk_mul_f32 v[32:33], v[32:33], v[0:1] op_sel_hi:[1,0]
	v_pk_mul_f32 v[34:35], v[34:35], v[0:1] op_sel_hi:[1,0]
	v_pk_mul_f32 v[32:33], v[96:97], v[32:33]
	v_pk_mul_f32 v[34:35], v[98:99], v[34:35]
	v_pk_mul_f32 v[36:37], v[36:37], v[0:1] op_sel_hi:[1,0]
	v_pk_mul_f32 v[38:39], v[38:39], v[0:1] op_sel_hi:[1,0]
	v_pk_mul_f32 v[36:37], v[92:93], v[36:37]
	v_pk_mul_f32 v[38:39], v[94:95], v[38:39]
	v_cvt_pk_bf16_f32 v32, v32, v33
	v_cvt_pk_bf16_f32 v33, v34, v35
	v_cvt_pk_bf16_f32 v34, v36, v37
	v_cvt_pk_bf16_f32 v35, v38, v39
	v_pk_mul_f32 v[40:41], v[40:41], v[0:1] op_sel_hi:[1,0]
	v_pk_mul_f32 v[42:43], v[42:43], v[0:1] op_sel_hi:[1,0]
	v_pk_mul_f32 v[40:41], v[88:89], v[40:41]
	v_pk_mul_f32 v[42:43], v[90:91], v[42:43]
	v_pk_mul_f32 v[44:45], v[44:45], v[0:1] op_sel_hi:[1,0]
	v_pk_mul_f32 v[46:47], v[46:47], v[0:1] op_sel_hi:[1,0]
	v_pk_mul_f32 v[44:45], v[84:85], v[44:45]
	v_pk_mul_f32 v[46:47], v[86:87], v[46:47]
	v_cvt_pk_bf16_f32 v40, v40, v41
	v_cvt_pk_bf16_f32 v41, v42, v43
	v_cvt_pk_bf16_f32 v42, v44, v45
	v_cvt_pk_bf16_f32 v43, v46, v47
	v_pk_mul_f32 v[16:17], v[16:17], v[0:1] op_sel_hi:[1,0]
	v_pk_mul_f32 v[18:19], v[18:19], v[0:1] op_sel_hi:[1,0]
	v_pk_mul_f32 v[16:17], v[80:81], v[16:17]
	v_pk_mul_f32 v[18:19], v[82:83], v[18:19]
	v_pk_mul_f32 v[20:21], v[20:21], v[0:1] op_sel_hi:[1,0]
	v_pk_mul_f32 v[22:23], v[22:23], v[0:1] op_sel_hi:[1,0]
	v_pk_mul_f32 v[20:21], v[10:11], v[20:21]
	v_pk_mul_f32 v[22:23], v[12:13], v[22:23]
	v_cvt_pk_bf16_f32 v16, v16, v17
	v_cvt_pk_bf16_f32 v17, v18, v19
	v_cvt_pk_bf16_f32 v18, v20, v21
	v_cvt_pk_bf16_f32 v19, v22, v23
	v_pk_mul_f32 v[24:25], v[24:25], v[0:1] op_sel_hi:[1,0]
	v_pk_mul_f32 v[26:27], v[26:27], v[0:1] op_sel_hi:[1,0]
	v_pk_mul_f32 v[24:25], v[6:7], v[24:25]
	v_pk_mul_f32 v[26:27], v[8:9], v[26:27]
	v_pk_mul_f32 v[14:15], v[14:15], v[0:1] op_sel_hi:[1,0]
	v_pk_mul_f32 v[30:31], v[30:31], v[0:1] op_sel_hi:[1,0]
	v_pk_mul_f32 v[14:15], v[2:3], v[14:15]
	v_pk_mul_f32 v[30:31], v[4:5], v[30:31]
	v_cvt_pk_bf16_f32 v24, v24, v25
	v_cvt_pk_bf16_f32 v25, v26, v27
	v_cvt_pk_bf16_f32 v26, v14, v15
	v_cvt_pk_bf16_f32 v27, v30, v31
	s_nop 1
	v_permlane32_swap_b32_e32 v64, v66
	v_permlane32_swap_b32_e32 v65, v67
	global_store_dwordx4 v[28:29], v[64:67], off
	v_permlane32_swap_b32_e32 v72, v74
	v_permlane32_swap_b32_e32 v73, v75
	global_store_dwordx4 v[28:29], v[72:75], off offset:32
	v_permlane32_swap_b32_e32 v48, v50
	v_permlane32_swap_b32_e32 v49, v51
	global_store_dwordx4 v[28:29], v[48:51], off offset:64
	v_permlane32_swap_b32_e32 v56, v58
	v_permlane32_swap_b32_e32 v57, v59
	global_store_dwordx4 v[28:29], v[56:59], off offset:96
	v_permlane32_swap_b32_e32 v32, v34
	v_permlane32_swap_b32_e32 v33, v35
	global_store_dwordx4 v[28:29], v[32:35], off offset:128
	v_permlane32_swap_b32_e32 v40, v42
	v_permlane32_swap_b32_e32 v41, v43
	global_store_dwordx4 v[28:29], v[40:43], off offset:160
	v_permlane32_swap_b32_e32 v16, v18
	v_permlane32_swap_b32_e32 v17, v19
	global_store_dwordx4 v[28:29], v[16:19], off offset:192
	v_permlane32_swap_b32_e32 v24, v26
	v_permlane32_swap_b32_e32 v25, v27
	global_store_dwordx4 v[28:29], v[24:27], off offset:224
	s_branch .LBB0_40

; #define LAS __attribute__((address_space(3)))
; __device__ __forceinline__ void gmlp_load(GmlpRegs& R, const bf16_t* zb, const bf16_t* wsb, const float* bsall, int u, int tid, int t, int h, int cb0) {
;     const int b = u / 96, rem = u % 96, n = rem / 6, g = rem % 6;
;     const bf16_t* zrows = zb + ((size_t)b * SEQ + n * 128) * NMIX0;
;     const bf16_t* urow = zrows + (size_t)t * NMIX0 + g * 128 + 4 * h;
; #pragma unroll
;     for (int i = 0; i < 8; ++i) R.uv[i] = *(const u32x2*)(urow + (cb0 + (i >> 2)) * 32 + 8 * (i & 3));
;     const bf16_t* wrow = wsb + (size_t)g * 128 * 128 + (size_t)t * 128 + 8 * h;
; #pragma unroll
;     for (int i = 0; i < 8; ++i) R.w[i] = *(const u32x4*)(wrow + 16 * i);
;     R.bias = bsall[g * 128 + t];
;     const bf16_t* vgp = zrows + (size_t)(tid >> 2) * NMIX0 + 768 + g * 128 + (tid & 3) * 32;
; #pragma unroll
;     for (int j = 0; j < 4; ++j) R.v[j] = *(const u32x4*)(vgp + 8 * j);
; __device__ __forceinline__ void gmlp_compute(LAS unsigned char* lds, const GmlpRegs& R, bf16_t* cat, int u, int tid, int lane, int t, int h, int cb0) {
;     constexpr int VP = 320, GOFF = 49152;
;     const int b = u / 96, rem = u % 96, n = rem / 6, g = rem % 6;
;     {
;         const int row = tid >> 2, qtr = tid & 3;
;         float ss = 0.f;
; #pragma unroll
;         for (int j = 0; j < 4; ++j)
; #pragma unroll
;             for (int e = 0; e < 4; ++e) { const float x = bf_lo(R.v[j][e]), y = bf_hi(R.v[j][e]); ss += x * x + y * y; }
;         ss += __shfl_xor(ss, 1); ss += __shfl_xor(ss, 2);
;         const float rs = rsqrtf(ss * (1.f / 128.f) + EPS);
.LBB0_69:
	s_add_i32 s10, s9, s44
	s_waitcnt vmcnt(4)
	v_lshlrev_b32_e32 v6, 16, v113
	v_and_b32_e32 v7, 0xffff0000, v113
	v_lshlrev_b32_e32 v10, 16, v111
	v_and_b32_e32 v11, 0xffff0000, v111
	v_lshlrev_b32_e32 v12, 16, v110
	v_and_b32_e32 v13, 0xffff0000, v110
	v_lshlrev_b32_e32 v8, 16, v112
	v_and_b32_e32 v9, 0xffff0000, v112
	s_cmpk_lt_i32 s10, 0x600
	v_pk_mul_f32 v[70:71], v[6:7], v[6:7]
	v_pk_mul_f32 v[74:75], v[10:11], v[10:11]
	v_pk_mul_f32 v[76:77], v[12:13], v[12:13]
	v_pk_mul_f32 v[72:73], v[8:9], v[8:9]
	s_cselect_b32 s11, s10, s9
	v_add_f32_e32 v70, v70, v71
	v_add_f32_e32 v71, v74, v75
	v_add_f32_e32 v74, v76, v77
	v_lshlrev_b32_e32 v20, 16, v106
	v_and_b32_e32 v21, 0xffff0000, v106
	v_add_f32_e32 v72, v72, v73
	s_mul_hi_i32 s23, s11, 0x2aaaaaab
	v_add_f32_e32 v71, v74, v71
	v_lshlrev_b32_e32 v18, 16, v107
	v_and_b32_e32 v19, 0xffff0000, v107
	v_pk_mul_f32 v[84:85], v[20:21], v[20:21]
	s_lshr_b32 s34, s23, 31
	s_ashr_i32 s23, s23, 4
	v_add_f32_e32 v71, v72, v71
	v_lshlrev_b32_e32 v16, 16, v108
	v_and_b32_e32 v17, 0xffff0000, v108
	v_pk_mul_f32 v[82:83], v[18:19], v[18:19]
	v_add_f32_e32 v73, v84, v85
	s_add_i32 s34, s23, s34
	v_add_f32_e32 v70, v70, v71
	v_and_b32_e32 v5, 0xffff0000, v101
	v_and_b32_e32 v4, 0xffff0000, v100
	v_lshlrev_b32_e32 v14, 16, v109
	v_and_b32_e32 v15, 0xffff0000, v109
	v_and_b32_e32 v27, 0xffff0000, v103
	v_and_b32_e32 v29, 0xffff0000, v102
	v_pk_mul_f32 v[80:81], v[16:17], v[16:17]
	v_add_f32_e32 v75, v82, v83
	s_mul_i32 s23, s34, 0x60
	v_add_f32_e32 v70, v73, v70
	v_lshlrev_b32_e32 v33, 16, v101
	v_lshlrev_b32_e32 v32, 16, v100
	v_lshlrev_b32_e32 v26, 16, v103
	v_lshlrev_b32_e32 v28, 16, v102
	v_pk_mul_f32 v[68:69], v[4:5], v[4:5]
	v_pk_mul_f32 v[78:79], v[14:15], v[14:15]
	v_mov_b32_e32 v92, v27
	v_mov_b32_e32 v93, v29
	v_add_f32_e32 v76, v80, v81
	s_sub_i32 s11, s11, s23
	v_add_f32_e32 v70, v75, v70
	v_and_b32_e32 v3, 0xffff0000, v99
	v_and_b32_e32 v2, 0xffff0000, v98
	v_and_b32_e32 v23, 0xffff0000, v105
	v_and_b32_e32 v25, 0xffff0000, v104
	v_mov_b32_e32 v90, v26
	v_mov_b32_e32 v91, v28
	v_mov_b32_e32 v192, v32
	v_mov_b32_e32 v193, v4
	v_mov_b32_e32 v4, v33
	v_pk_fma_f32 v[32:33], v[32:33], v[32:33], v[68:69]
	v_pk_mul_f32 v[68:69], v[92:93], v[92:93]
	v_add_f32_e32 v77, v78, v79
	s_mul_i32 s23, s11, 43
	v_add_f32_e32 v70, v76, v70
	v_lshlrev_b32_e32 v31, 16, v99
	v_lshlrev_b32_e32 v30, 16, v98
	v_lshlrev_b32_e32 v22, 16, v105
	v_lshlrev_b32_e32 v24, 16, v104
	v_pk_mul_f32 v[66:67], v[2:3], v[2:3]
	v_mov_b32_e32 v88, v23
	v_mov_b32_e32 v89, v25
	v_pk_fma_f32 v[68:69], v[90:91], v[90:91], v[68:69]
	s_bfe_u32 s36, s23, 0x1000f
	s_bfe_u32 s23, s23, 0x80008
	v_add_f32_e32 v70, v77, v70
	v_mov_b32_e32 v86, v22
	v_mov_b32_e32 v87, v24
	v_mov_b32_e32 v178, v30
	v_mov_b32_e32 v179, v2
	v_mov_b32_e32 v2, v31
	v_pk_fma_f32 v[30:31], v[30:31], v[30:31], v[66:67]
	v_pk_mul_f32 v[66:67], v[88:89], v[88:89]
	s_add_i32 s23, s23, s36
	v_add_f32_e32 v69, v69, v70
	v_pk_fma_f32 v[66:67], v[86:87], v[86:87], v[66:67]
	s_sext_i32_i8 s37, s23
	s_mul_i32 s23, s23, 6
	v_add_f32_e32 v68, v68, v69
	s_ashr_i32 s35, s34, 31
	s_sub_i32 s36, s11, s23
	s_lshl_b32 s11, s37, 7
	v_add_f32_e32 v67, v67, v68
	s_lshl_b64 s[34:35], s[34:35], 11
	s_ashr_i32 s37, s11, 31
	v_add_f32_e32 v66, v66, v67
	s_add_u32 s11, s34, s11
	v_add_f32_e32 v30, v30, v66
	s_addc_u32 s34, s35, s37
	v_add_f32_e32 v30, v31, v30
	s_mul_hi_u32 s35, s11, 0xe00
	s_mulk_i32 s34, 0xe00
	v_add_f32_e32 v30, v32, v30
	s_mulk_i32 s11, 0xe00
	s_add_i32 s35, s35, s34
	v_add_f32_e32 v100, v33, v30
	s_sext_i32_i8 s23, s36
	s_add_u32 s34, s24, s11
	ds_bpermute_b32 v101, v219, v100
	s_addc_u32 s35, s25, s35
	s_lshl_b32 s38, s23, 7
	s_bfe_i64 s[36:37], s[36:37], 0x80000
	s_ashr_i32 s39, s38, 31
	v_add_u32_e32 v32, s38, v114
	s_lshl_b64 s[36:37], s[36:37], 15
	v_lshl_add_u64 v[30:31], s[34:35], 0, v[118:119]
	v_lshl_add_u64 v[98:99], s[34:35], 0, v[120:121]
	s_lshl_b64 s[34:35], s[38:39], 1
	v_ashrrev_i32_e32 v33, 31, v32
	v_mov_b32_e32 v125, v1
	v_lshl_add_u64 v[66:67], v[122:123], 0, s[36:37]
	v_lshl_add_u64 v[32:33], v[32:33], 2, s[4:5]
	v_lshl_add_u64 v[98:99], v[98:99], 0, s[34:35]
	global_load_dwordx4 v[78:81], v[66:67], off
	global_load_dwordx4 v[82:85], v[66:67], off offset:32
	global_load_dwordx4 v[86:89], v[66:67], off offset:64
	global_load_dwordx4 v[90:93], v[66:67], off offset:96
	global_load_dwordx4 v[94:97], v[66:67], off offset:128
	global_load_dwordx4 v[70:73], v[66:67], off offset:160
	global_load_dwordx4 v[74:77], v[66:67], off offset:192
	s_nop 0
	global_load_dwordx4 v[66:69], v[66:67], off offset:224
	s_mul_hi_i32 s8, s9, 0x2aaaaaab
	global_load_dword v200, v[32:33], off
	v_lshl_add_u64 v[32:33], v[98:99], 0, v[124:125]
	s_waitcnt lgkmcnt(0)
	v_add_f32_e32 v125, v100, v101
	global_load_dwordx4 v[98:101], v[32:33], off offset:1584
	global_load_dwordx4 v[102:105], v[32:33], off offset:1568
	global_load_dwordx4 v[106:109], v[32:33], off offset:1552
	global_load_dwordx4 v[110:113], v[32:33], off offset:1536
	ds_bpermute_b32 v32, v220, v125
	s_lshr_b32 s11, s8, 31
	s_ashr_i32 s8, s8, 4
	s_add_i32 s8, s8, s11
	s_mul_i32 s11, s8, 0xffffffa0
	s_add_i32 s9, s9, s11
	s_mul_i32 s11, s9, 43
	s_waitcnt lgkmcnt(0)
; #define LAS __attribute__((address_space(3)))
; __device__ __forceinline__ unsigned pk_bf16(float lo, float hi) { f32x2 v = {lo, hi}; bf16x2_t b = __builtin_convertvector(v, bf16x2_t); return __builtin_bit_cast(unsigned, b); }
; __device__ __forceinline__ void gmlp_load(GmlpRegs& R, const bf16_t* zb, const bf16_t* wsb, const float* bsall, int u, int tid, int t, int h, int cb0) {
;     ...
;     for (int i = 0; i < 8; ++i) R.uv[i] = *(const u32x2*)(urow + (cb0 + (i >> 2)) * 32 + 8 * (i & 3));
; __device__ __forceinline__ void gmlp_compute(LAS unsigned char* lds, const GmlpRegs& R, bf16_t* cat, int u, int tid, int lane, int t, int h, int cb0) {
;     ...
;         ss += __shfl_xor(ss, 1); ss += __shfl_xor(ss, 2);
;         const float rs = rsqrtf(ss * (1.f / 128.f) + EPS);
;         LAS const unsigned char* gp = lds + GOFF + (g * 128 + qtr * 32) * 4;
;         LAS unsigned char* dst = lds + row * VP + qtr * 64;
; #pragma unroll
;         for (int j = 0; j < 4; ++j) {
;             const f32x4 g0 = *(LAS const f32x4*)(gp + 32 * j), g1 = *(LAS const f32x4*)(gp + 32 * j + 16);
;             u32x4 o;
;             o.x = pk_bf16(bf_lo(R.v[j].x) * rs * g0[0], bf_hi(R.v[j].x) * rs * g0[1]); o.y = pk_bf16(bf_lo(R.v[j].y) * rs * g0[2], bf_hi(R.v[j].y) * rs * g0[3]);
;             o.z = pk_bf16(bf_lo(R.v[j].z) * rs * g1[0], bf_hi(R.v[j].z) * rs * g1[1]); o.w = pk_bf16(bf_lo(R.v[j].w) * rs * g1[2], bf_hi(R.v[j].w) * rs * g1[3]);
;             *(LAS u32x4*)(dst + 16 * j) = o;
;         }
;     }
	v_add_f32_e32 v125, v125, v32
	s_bfe_u32 s23, s11, 0x1000f
	s_bfe_u32 s11, s11, 0x80008
	v_fmamk_f32 v125, v125, 0x3c000000, v182
	s_add_i32 s23, s11, s23
	v_mul_f32_e32 v194, 0x4b800000, v125
	v_cmp_gt_f32_e32 vcc, s89, v125
	s_mul_i32 s11, s23, 6
	v_lshl_add_u64 v[30:31], v[30:31], 0, s[34:35]
	v_cndmask_b32_e32 v125, v125, v194, vcc
	s_sub_i32 s9, s9, s11
	v_rsq_f32_e32 v125, v125
	v_lshl_add_u64 v[30:31], v[30:31], 0, v[0:1]
	s_sext_i32_i8 s11, s9
	v_lshl_add_u64 v[30:31], v[30:31], 0, s[6:7]
	v_lshl_add_u32 v149, s11, 9, v117
	v_lshlrev_b32_e32 v136, 16, v160
	v_and_b32_e32 v137, 0xffff0000, v160
	v_lshlrev_b32_e32 v138, 16, v161
	v_and_b32_e32 v139, 0xffff0000, v161
	v_lshlrev_b32_e32 v140, 16, v162
	v_and_b32_e32 v141, 0xffff0000, v162
	v_lshlrev_b32_e32 v142, 16, v163
	v_and_b32_e32 v143, 0xffff0000, v163
	v_lshlrev_b32_e32 v144, 16, v164
	v_and_b32_e32 v145, 0xffff0000, v164
	v_lshlrev_b32_e32 v146, 16, v165
	v_and_b32_e32 v147, 0xffff0000, v165
	global_load_dwordx2 v[160:161], v[30:31], off
	global_load_dwordx2 v[162:163], v[30:31], off offset:16
	global_load_dwordx2 v[164:165], v[30:31], off offset:32
	global_load_dwordx2 v[150:151], v[30:31], off offset:48
	global_load_dwordx2 v[152:153], v[30:31], off offset:64
	global_load_dwordx2 v[154:155], v[30:31], off offset:80
	global_load_dwordx2 v[156:157], v[30:31], off offset:96
	global_load_dwordx2 v[158:159], v[30:31], off offset:112
	ds_read_b128 v[30:33], v149 offset:49152
	ds_read_b128 v[166:169], v149 offset:49168
	ds_read_b128 v[170:173], v149 offset:49184
	ds_read_b128 v[174:177], v149 offset:49200
	v_mul_f32_e32 v194, 0x45800000, v125
	v_cndmask_b32_e32 v194, v125, v194, vcc
	v_pk_mul_f32 v[12:13], v[194:195], v[12:13] op_sel_hi:[0,1]
	v_pk_mul_f32 v[10:11], v[194:195], v[10:11] op_sel_hi:[0,1]
	v_pk_mul_f32 v[8:9], v[194:195], v[8:9] op_sel_hi:[0,1]
	v_pk_mul_f32 v[6:7], v[194:195], v[6:7] op_sel_hi:[0,1]
	v_pk_mul_f32 v[20:21], v[194:195], v[20:21] op_sel_hi:[0,1]
	v_pk_mul_f32 v[18:19], v[194:195], v[18:19] op_sel_hi:[0,1]
	v_pk_mul_f32 v[16:17], v[194:195], v[16:17] op_sel_hi:[0,1]
	v_pk_mul_f32 v[14:15], v[194:195], v[14:15] op_sel_hi:[0,1]
	v_pk_mul_f32 v[28:29], v[194:195], v[28:29] op_sel_hi:[0,1]
	v_pk_mul_f32 v[26:27], v[194:195], v[26:27] op_sel_hi:[0,1]
	v_pk_mul_f32 v[24:25], v[194:195], v[24:25] op_sel_hi:[0,1]
	v_pk_mul_f32 v[22:23], v[194:195], v[22:23] op_sel_hi:[0,1]
	v_pk_mul_f32 v[178:179], v[194:195], v[178:179] op_sel_hi:[0,1]
	v_pk_mul_f32 v[202:203], v[194:195], v[2:3] op_sel_hi:[0,1]
	v_pk_mul_f32 v[192:193], v[194:195], v[192:193] op_sel_hi:[0,1]
	v_pk_mul_f32 v[194:195], v[194:195], v[4:5] op_sel_hi:[0,1]
	s_waitcnt lgkmcnt(3)
	v_pk_mul_f32 v[2:3], v[30:31], v[12:13]
	v_pk_mul_f32 v[4:5], v[32:33], v[10:11]
	s_waitcnt lgkmcnt(2)
	v_pk_mul_f32 v[8:9], v[166:167], v[8:9]
	v_pk_mul_f32 v[6:7], v[168:169], v[6:7]
	s_waitcnt lgkmcnt(1)
	v_pk_mul_f32 v[10:11], v[170:171], v[20:21]
	v_pk_mul_f32 v[12:13], v[172:173], v[18:19]
	s_waitcnt lgkmcnt(0)
	v_pk_mul_f32 v[16:17], v[174:175], v[16:17]
	v_pk_mul_f32 v[14:15], v[176:177], v[14:15]
	v_cvt_pk_bf16_f32 v2, v2, v3
	v_cvt_pk_bf16_f32 v3, v4, v5
	v_cvt_pk_bf16_f32 v4, v8, v9
	v_cvt_pk_bf16_f32 v5, v6, v7
	v_cvt_pk_bf16_f32 v6, v10, v11
	v_cvt_pk_bf16_f32 v7, v12, v13
	v_cvt_pk_bf16_f32 v8, v16, v17
	v_cvt_pk_bf16_f32 v9, v14, v15
	ds_write_b128 v196, v[2:5]
	ds_write_b128 v196, v[6:9] offset:16
	ds_read_b128 v[2:5], v149 offset:49216
	ds_read_b128 v[6:9], v149 offset:49232
	v_lshlrev_b32_e32 v168, 16, v132
	v_and_b32_e32 v169, 0xffff0000, v132
	v_lshlrev_b32_e32 v170, 16, v133
	s_waitcnt lgkmcnt(1)
	v_pk_mul_f32 v[2:3], v[2:3], v[28:29]
	v_pk_mul_f32 v[4:5], v[4:5], v[26:27]
	s_waitcnt lgkmcnt(0)
	v_pk_mul_f32 v[6:7], v[6:7], v[24:25]
	v_pk_mul_f32 v[8:9], v[8:9], v[22:23]
	v_cvt_pk_bf16_f32 v2, v2, v3
	v_cvt_pk_bf16_f32 v3, v4, v5
	v_cvt_pk_bf16_f32 v4, v6, v7
	v_cvt_pk_bf16_f32 v5, v8, v9
	ds_write_b128 v196, v[2:5] offset:32
	ds_read_b128 v[2:5], v149 offset:49248
	ds_read_b128 v[6:9], v149 offset:49264
	v_and_b32_e32 v171, 0xffff0000, v133
	s_ashr_i32 s9, s8, 31
	s_lshl_b64 s[34:35], s[8:9], 11
	s_waitcnt lgkmcnt(1)
	v_pk_mul_f32 v[2:3], v[178:179], v[2:3]
	v_pk_mul_f32 v[4:5], v[202:203], v[4:5]
	s_waitcnt lgkmcnt(0)
	v_pk_mul_f32 v[6:7], v[192:193], v[6:7]
	v_pk_mul_f32 v[8:9], v[194:195], v[8:9]
	v_cvt_pk_bf16_f32 v2, v2, v3
	v_cvt_pk_bf16_f32 v3, v4, v5
	v_cvt_pk_bf16_f32 v4, v6, v7
	v_cvt_pk_bf16_f32 v5, v8, v9
	ds_write_b128 v196, v[2:5] offset:48
	s_waitcnt lgkmcnt(0)
	s_barrier
; #define LAS __attribute__((address_space(3)))
; #define MFMA32(a, b, c) __builtin_amdgcn_mfma_f32_32x32x16_bf16((a), (b), (c), 0, 0, 0)
; __device__ __forceinline__ void gmlp_compute(LAS unsigned char* lds, const GmlpRegs& R, bf16_t* cat, int u, int tid, int lane, int t, int h, int cb0) {
;     ...
;     const int q4 = (lane & 15) >> 2, p4 = lane & 3, blk = (lane >> 4) & 1;
;     LAS const char* vb = (LAS const char*)lds + (8 * h + q4) * VP + (cb0 * 32 + 16 * blk) * 2 + 8 * p4;
;     f32x16 a0, a1;
; #pragma unroll
;     for (int i = 0; i < 16; ++i) { a0[i] = 0.f; a1[i] = 0.f; }
; #pragma unroll
;     for (int ks = 0; ks < 8; ++ks) {
;         const bf16x8 wf = __builtin_bit_cast(bf16x8, R.w[ks]);
;         const bf16x8 v0 = vtr8(vb + ks * 16 * VP, 4 * VP), v1 = vtr8(vb + ks * 16 * VP + 64, 4 * VP);
;         a0 = MFMA32(v0, wf, a0); a1 = MFMA32(v1, wf, a1);
	ds_read_b64_tr_b16 v[2:3], v198
	ds_read_b64_tr_b16 v[4:5], v198 offset:1280
	ds_read_b64_tr_b16 v[20:21], v198 offset:1344
	ds_read_b64_tr_b16 v[18:19], v198 offset:64
	ds_read_b64_tr_b16 v[172:173], v198 offset:5120
	s_waitcnt lgkmcnt(3)
	v_mfma_f32_32x32x16_bf16 v[2:17], v[2:5], v[62:65], 0
	s_sext_i32_i8 s8, s23
	s_lshl_b32 s8, s8, 7
	s_ashr_i32 s23, s8, 31
	s_lshl_b32 s36, s11, 7
	s_add_u32 s34, s8, s34
	s_addc_u32 s35, s23, s35
	s_ashr_i32 s37, s36, 31
	s_waitcnt lgkmcnt(1)
	v_mfma_f32_32x32x16_bf16 v[18:33], v[18:21], v[62:65], 0
	ds_read_b64_tr_b16 v[174:175], v198 offset:6400
	ds_read_b64_tr_b16 v[64:65], v198 offset:6464
	ds_read_b64_tr_b16 v[62:63], v198 offset:5184
	v_lshlrev_b32_e32 v176, 16, v128
	v_and_b32_e32 v177, 0xffff0000, v128
	v_lshlrev_b32_e32 v178, 16, v129
	v_and_b32_e32 v179, 0xffff0000, v129
	v_lshlrev_b32_e32 v192, 16, v126
	v_and_b32_e32 v193, 0xffff0000, v126
	s_waitcnt lgkmcnt(2)
	v_mfma_f32_32x32x16_bf16 v[2:17], v[172:175], v[58:61], v[2:17]
	v_lshlrev_b32_e32 v172, 16, v130
	v_and_b32_e32 v173, 0xffff0000, v130
	v_lshlrev_b32_e32 v174, 16, v131
	v_and_b32_e32 v175, 0xffff0000, v131
	ds_read_b64_tr_b16 v[130:131], v198 offset:10240
	v_lshlrev_b32_e32 v194, 16, v127
	v_and_b32_e32 v195, 0xffff0000, v127
	s_waitcnt lgkmcnt(1)
	v_mfma_f32_32x32x16_bf16 v[18:33], v[62:65], v[58:61], v[18:33]
	ds_read_b64_tr_b16 v[132:133], v198 offset:11520
	ds_read_b64_tr_b16 v[60:61], v198 offset:11584
	ds_read_b64_tr_b16 v[58:59], v198 offset:10304
	ds_read_b64_tr_b16 v[62:63], v198 offset:15360
	v_lshlrev_b32_e32 v148, 16, v134
	v_and_b32_e32 v149, 0xffff0000, v134
	v_lshlrev_b32_e32 v166, 16, v135
	v_and_b32_e32 v167, 0xffff0000, v135
	s_mov_b32 s9, s10
	s_waitcnt lgkmcnt(3)
	v_mfma_f32_32x32x16_bf16 v[2:17], v[130:133], v[54:57], v[2:17]
	s_cmpk_gt_i32 s10, 0x5ff
	s_waitcnt vmcnt(4)
	v_mov_b64_e32 v[134:135], v[150:151]
	s_waitcnt vmcnt(3)
	v_mov_b64_e32 v[132:133], v[152:153]
	s_waitcnt vmcnt(2)
	v_mov_b64_e32 v[130:131], v[154:155]
	s_waitcnt lgkmcnt(1)
	v_mfma_f32_32x32x16_bf16 v[18:33], v[58:61], v[54:57], v[18:33]
	ds_read_b64_tr_b16 v[64:65], v198 offset:16640
	ds_read_b64_tr_b16 v[56:57], v198 offset:16704
	ds_read_b64_tr_b16 v[54:55], v198 offset:15424
	ds_read_b64_tr_b16 v[58:59], v198 offset:20480
	s_waitcnt lgkmcnt(3)
	v_mfma_f32_32x32x16_bf16 v[2:17], v[62:65], v[50:53], v[2:17]
	v_mov_b64_e32 v[62:63], v[78:79]
	v_mov_b64_e32 v[64:65], v[80:81]
	s_waitcnt lgkmcnt(1)
	v_mfma_f32_32x32x16_bf16 v[18:33], v[54:57], v[50:53], v[18:33]
	ds_read_b64_tr_b16 v[60:61], v198 offset:21760
	ds_read_b64_tr_b16 v[52:53], v198 offset:21824
	ds_read_b64_tr_b16 v[50:51], v198 offset:20544
	ds_read_b64_tr_b16 v[54:55], v198 offset:25600
	s_waitcnt lgkmcnt(3)
	v_mfma_f32_32x32x16_bf16 v[2:17], v[58:61], v[46:49], v[2:17]
	v_mov_b64_e32 v[58:59], v[82:83]
	v_mov_b64_e32 v[60:61], v[84:85]
	s_waitcnt lgkmcnt(1)
	v_mfma_f32_32x32x16_bf16 v[18:33], v[50:53], v[46:49], v[18:33]
	v_lshl_add_u64 v[50:51], s[34:35], 0, v[114:115]
	v_lshlrev_b64 v[50:51], 11, v[50:51]
	ds_read_b64_tr_b16 v[56:57], v198 offset:26880
	ds_read_b64_tr_b16 v[48:49], v198 offset:26944
	ds_read_b64_tr_b16 v[46:47], v198 offset:25664
	v_lshl_add_u64 v[50:51], s[12:13], 0, v[50:51]
	v_lshl_add_u64 v[50:51], s[36:37], 1, v[50:51]
	v_lshl_add_u64 v[50:51], v[50:51], 0, v[0:1]
	v_lshl_add_u64 v[206:207], v[50:51], 0, s[6:7]
	ds_read_b64_tr_b16 v[50:51], v198 offset:30720
	s_waitcnt lgkmcnt(3)
	v_mfma_f32_32x32x16_bf16 v[2:17], v[54:57], v[42:45], v[2:17]
	v_mov_b64_e32 v[54:55], v[86:87]
	v_mov_b64_e32 v[56:57], v[88:89]
	s_waitcnt lgkmcnt(1)
	v_mfma_f32_32x32x16_bf16 v[18:33], v[46:49], v[42:45], v[18:33]
	ds_read_b64_tr_b16 v[52:53], v198 offset:32000
	ds_read_b64_tr_b16 v[44:45], v198 offset:32064
	ds_read_b64_tr_b16 v[42:43], v198 offset:30784
	ds_read_b64_tr_b16 v[126:127], v198 offset:35840
	ds_read_b64_tr_b16 v[128:129], v198 offset:37120
	ds_read_b64_tr_b16 v[204:205], v198 offset:37184
	ds_read_b64_tr_b16 v[202:203], v198 offset:35904
	v_mov_b64_e32 v[46:47], v[94:95]
	v_mov_b64_e32 v[48:49], v[96:97]
	s_waitcnt lgkmcnt(6)
; __device__ __forceinline__ unsigned pk_bf16(float lo, float hi) { f32x2 v = {lo, hi}; bf16x2_t b = __builtin_convertvector(v, bf16x2_t); return __builtin_bit_cast(unsigned, b); }
; #define MFMA32(a, b, c) __builtin_amdgcn_mfma_f32_32x32x16_bf16((a), (b), (c), 0, 0, 0)
; __device__ __forceinline__ void gmlp_compute(LAS unsigned char* lds, const GmlpRegs& R, bf16_t* cat, int u, int tid, int lane, int t, int h, int cb0) {
;     ...
;         a0 = MFMA32(v0, wf, a0); a1 = MFMA32(v1, wf, a1);
;     }
;     bf16_t* orow = cat + ((size_t)b * SEQ + n * 128 + t) * DM + g * 128 + 4 * h;
;     const float bias = R.bias;
; #pragma unroll
;     for (int cbi = 0; cbi < 2; ++cbi)
; #pragma unroll
;         for (int gq = 0; gq < 4; ++gq) {
;             const int c0 = (cb0 + cbi) * 32 + 8 * gq;
;             const u32x2 uu = R.uv[cbi * 4 + gq];
;             const f32x16& a = cbi ? a1 : a0;
;             u32x2 wv; wv.x = pk_bf16(bf_lo(uu.x) * (a[4 * gq] + bias), bf_hi(uu.x) * (a[4 * gq + 1] + bias));
;             wv.y = pk_bf16(bf_lo(uu.y) * (a[4 * gq + 2] + bias), bf_hi(uu.y) * (a[4 * gq + 3] + bias));
;             *(u32x2*)(orow + c0) = wv;
;         }
;     __syncthreads();
	v_mfma_f32_32x32x16_bf16 v[2:17], v[50:53], v[38:41], v[2:17]
	v_mov_b64_e32 v[50:51], v[90:91]
	v_mov_b64_e32 v[52:53], v[92:93]
	s_waitcnt lgkmcnt(4)
	v_mfma_f32_32x32x16_bf16 v[18:33], v[42:45], v[38:41], v[18:33]
	v_mov_b64_e32 v[42:43], v[70:71]
	v_mov_b64_e32 v[38:39], v[74:75]
	v_mov_b64_e32 v[44:45], v[72:73]
	v_mov_b64_e32 v[40:41], v[76:77]
	s_waitcnt lgkmcnt(2)
	v_mfma_f32_32x32x16_bf16 v[2:17], v[126:129], v[34:37], v[2:17]
	s_waitcnt vmcnt(1)
	v_mov_b64_e32 v[128:129], v[156:157]
	s_waitcnt vmcnt(0)
	v_mov_b64_e32 v[126:127], v[158:159]
	s_waitcnt lgkmcnt(0)
	v_mfma_f32_32x32x16_bf16 v[18:33], v[202:205], v[34:37], v[18:33]
	s_nop 5
	v_add_f32_e64 v2, v116, v2
	v_add_f32_e64 v3, v116, v3
	v_add_f32_e64 v4, v116, v4
	v_add_f32_e64 v5, v116, v5
	v_mov_b64_e32 v[34:35], v[66:67]
	v_pk_add_f32 v[6:7], v[116:117], v[6:7] op_sel_hi:[0,1]
	v_pk_add_f32 v[8:9], v[116:117], v[8:9] op_sel_hi:[0,1]
	v_pk_add_f32 v[10:11], v[116:117], v[10:11] op_sel_hi:[0,1]
	v_pk_add_f32 v[12:13], v[116:117], v[12:13] op_sel_hi:[0,1]
	v_pk_add_f32 v[14:15], v[116:117], v[14:15] op_sel_hi:[0,1]
	v_pk_add_f32 v[16:17], v[116:117], v[16:17] op_sel_hi:[0,1]
	v_pk_add_f32 v[18:19], v[116:117], v[18:19] op_sel_hi:[0,1]
	v_pk_add_f32 v[20:21], v[116:117], v[20:21] op_sel_hi:[0,1]
	v_pk_add_f32 v[22:23], v[116:117], v[22:23] op_sel_hi:[0,1]
	v_pk_add_f32 v[24:25], v[116:117], v[24:25] op_sel_hi:[0,1]
	v_pk_add_f32 v[26:27], v[116:117], v[26:27] op_sel_hi:[0,1]
	v_pk_add_f32 v[28:29], v[116:117], v[28:29] op_sel_hi:[0,1]
	v_pk_add_f32 v[30:31], v[116:117], v[30:31] op_sel_hi:[0,1]
	v_pk_add_f32 v[32:33], v[116:117], v[32:33] op_sel_hi:[0,1]
	v_pk_mul_f32 v[2:3], v[2:3], v[136:137]
	v_pk_mul_f32 v[4:5], v[4:5], v[138:139]
	v_mov_b64_e32 v[36:37], v[68:69]
	v_mov_b32_e32 v116, v200
	v_pk_mul_f32 v[6:7], v[6:7], v[140:141]
	v_pk_mul_f32 v[8:9], v[8:9], v[142:143]
	v_pk_mul_f32 v[10:11], v[10:11], v[144:145]
	v_pk_mul_f32 v[12:13], v[12:13], v[146:147]
	v_pk_mul_f32 v[14:15], v[14:15], v[148:149]
	v_pk_mul_f32 v[16:17], v[16:17], v[166:167]
	v_pk_mul_f32 v[18:19], v[18:19], v[168:169]
	v_pk_mul_f32 v[20:21], v[20:21], v[170:171]
	v_pk_mul_f32 v[22:23], v[22:23], v[172:173]
	v_pk_mul_f32 v[24:25], v[24:25], v[174:175]
	v_pk_mul_f32 v[26:27], v[26:27], v[176:177]
	v_pk_mul_f32 v[28:29], v[28:29], v[178:179]
	v_pk_mul_f32 v[30:31], v[30:31], v[192:193]
	v_pk_mul_f32 v[32:33], v[32:33], v[194:195]
	v_cvt_pk_bf16_f32 v2, v2, v3
	v_cvt_pk_bf16_f32 v3, v4, v5
	v_cvt_pk_bf16_f32 v4, v6, v7
	v_cvt_pk_bf16_f32 v5, v8, v9
	v_cvt_pk_bf16_f32 v6, v10, v11
	v_cvt_pk_bf16_f32 v7, v12, v13
	v_cvt_pk_bf16_f32 v8, v14, v15
	v_cvt_pk_bf16_f32 v9, v16, v17
	v_cvt_pk_bf16_f32 v10, v18, v19
	v_cvt_pk_bf16_f32 v11, v20, v21
	v_cvt_pk_bf16_f32 v12, v22, v23
	v_cvt_pk_bf16_f32 v13, v24, v25
	v_cvt_pk_bf16_f32 v14, v26, v27
	v_cvt_pk_bf16_f32 v15, v28, v29
	v_cvt_pk_bf16_f32 v16, v30, v31
	v_cvt_pk_bf16_f32 v17, v32, v33
	s_nop 1
	v_permlane32_swap_b32_e32 v2, v4
	v_permlane32_swap_b32_e32 v3, v5
	v_permlane32_swap_b32_e32 v6, v8
	v_permlane32_swap_b32_e32 v7, v9
	v_permlane32_swap_b32_e32 v10, v12
	v_permlane32_swap_b32_e32 v11, v13
	v_permlane32_swap_b32_e32 v14, v16
	v_permlane32_swap_b32_e32 v15, v17
	v_and_b32_e32 v18, 32, v197
	v_lshrrev_b32_e32 v18, 2, v18
	v_add_co_u32_e32 v206, vcc, v18, v206
	s_nop 1
	v_addc_co_u32_e32 v207, vcc, 0, v207, vcc
	global_store_dwordx4 v[206:207], v[2:5], off
	global_store_dwordx4 v[206:207], v[6:9], off offset:32
	global_store_dwordx4 v[206:207], v[10:13], off offset:64
	global_store_dwordx4 v[206:207], v[14:17], off offset:96
	s_barrier
	s_cbranch_scc0 .LBB0_69

; __device__ __forceinline__ unsigned pk_bf16(float lo, float hi) { f32x2 v = {lo, hi}; bf16x2_t b = __builtin_convertvector(v, bf16x2_t); return __builtin_bit_cast(unsigned, b); }
; template <bool DIFF>
; __device__ __forceinline__ void attn_unit(LAS unsigned char* lds, const bf16_t* Qp, int ldq, const bf16_t* Kp, const bf16_t* Vp, int ldkv,
;                                           bf16_t* Op, int qb, float lam, const float* subln, const float sbound, const int tid) {
;     ...
;     l = xor32_sum(l);
;     const float inv = 1.f / l;
;     if (!DIFF) {
;         bf16_t* orow = Op + (size_t)(sq * 32 + r) * DM + c * 64 + 4 * h;
; #pragma unroll
;         for (int d = 0; d < NDV; ++d)
; #pragma unroll
;             for (int g = 0; g < 4; ++g) {
;                 u32x2 wv; wv.x = pk_bf16(o[d][4 * g] * inv, o[d][4 * g + 1] * inv); wv.y = pk_bf16(o[d][4 * g + 2] * inv, o[d][4 * g + 3] * inv);
;                 *(u32x2*)(orow + d * 32 + 8 * g) = wv;
;             }
.LBB0_72:
	v_mov_b32_e32 v0, v167
	s_lshl_b64 s[6:7], s[8:9], 11
	s_nop 0
	v_permlane32_swap_b32_e32 v167, v0
	s_add_u32 s8, s12, s6
	v_add_f32_e32 v0, v167, v0
	s_addc_u32 s9, s13, s7
	v_div_scale_f32 v34, s[6:7], v0, v0, 1.0
	v_rcp_f32_e32 v35, v34
	s_lshl_b32 s6, s38, 1
	s_add_u32 s6, s8, s6
	s_addc_u32 s7, s9, 0
	v_fma_f32 v36, -v34, v35, 1.0
	v_fmac_f32_e32 v35, v36, v35
	v_div_scale_f32 v36, vcc, 1.0, v0, 1.0
	v_mul_f32_e32 v37, v36, v35
	v_fma_f32 v38, -v34, v37, v36
	v_fmac_f32_e32 v37, v38, v35
	v_fma_f32 v34, -v34, v37, v36
	v_div_fmas_f32 v34, v34, v35, v37
	v_div_fixup_f32 v34, v34, v0, 1.0
	v_lshlrev_b32_e32 v0, 11, v155
	v_lshl_add_u64 v[36:37], s[6:7], 0, v[0:1]
	v_lshl_add_u64 v[36:37], s[10:11], 1, v[36:37]
	v_mov_b32_e32 v155, v1
	v_lshl_add_u64 v[36:37], v[36:37], 0, v[154:155]
	v_and_b32_e32 v38, 32, v197
	v_lshrrev_b32_e32 v38, 2, v38
	v_add_co_u32_e32 v36, vcc, v38, v36
	s_nop 1
	v_addc_co_u32_e32 v37, vcc, 0, v37, vcc
	v_pk_mul_f32 v[2:3], v[2:3], v[34:35] op_sel_hi:[1,0]
	v_pk_mul_f32 v[4:5], v[4:5], v[34:35] op_sel_hi:[1,0]
	v_pk_mul_f32 v[6:7], v[6:7], v[34:35] op_sel_hi:[1,0]
	v_pk_mul_f32 v[8:9], v[8:9], v[34:35] op_sel_hi:[1,0]
	v_cvt_pk_bf16_f32 v2, v2, v3
	v_cvt_pk_bf16_f32 v3, v4, v5
	v_cvt_pk_bf16_f32 v4, v6, v7
	v_cvt_pk_bf16_f32 v5, v8, v9
	v_pk_mul_f32 v[10:11], v[10:11], v[34:35] op_sel_hi:[1,0]
	v_pk_mul_f32 v[12:13], v[12:13], v[34:35] op_sel_hi:[1,0]
	v_pk_mul_f32 v[14:15], v[14:15], v[34:35] op_sel_hi:[1,0]
	v_pk_mul_f32 v[16:17], v[16:17], v[34:35] op_sel_hi:[1,0]
	v_cvt_pk_bf16_f32 v10, v10, v11
	v_cvt_pk_bf16_f32 v11, v12, v13
	v_cvt_pk_bf16_f32 v12, v14, v15
	v_cvt_pk_bf16_f32 v13, v16, v17
	v_pk_mul_f32 v[18:19], v[18:19], v[34:35] op_sel_hi:[1,0]
	v_pk_mul_f32 v[20:21], v[20:21], v[34:35] op_sel_hi:[1,0]
	v_pk_mul_f32 v[22:23], v[22:23], v[34:35] op_sel_hi:[1,0]
	v_pk_mul_f32 v[24:25], v[24:25], v[34:35] op_sel_hi:[1,0]
	v_cvt_pk_bf16_f32 v18, v18, v19
	v_cvt_pk_bf16_f32 v19, v20, v21
	v_cvt_pk_bf16_f32 v20, v22, v23
	v_cvt_pk_bf16_f32 v21, v24, v25
	v_pk_mul_f32 v[26:27], v[26:27], v[34:35] op_sel_hi:[1,0]
	v_pk_mul_f32 v[28:29], v[28:29], v[34:35] op_sel_hi:[1,0]
	v_pk_mul_f32 v[30:31], v[30:31], v[34:35] op_sel_hi:[1,0]
	v_pk_mul_f32 v[32:33], v[32:33], v[34:35] op_sel_hi:[1,0]
	v_cvt_pk_bf16_f32 v26, v26, v27
	v_cvt_pk_bf16_f32 v27, v28, v29
	v_cvt_pk_bf16_f32 v28, v30, v31
	v_cvt_pk_bf16_f32 v29, v32, v33
	s_nop 1
	v_permlane32_swap_b32_e32 v2, v4
	v_permlane32_swap_b32_e32 v3, v5
	global_store_dwordx4 v[36:37], v[2:5], off offset:1536
	v_permlane32_swap_b32_e32 v10, v12
	v_permlane32_swap_b32_e32 v11, v13
	global_store_dwordx4 v[36:37], v[10:13], off offset:1568
	v_permlane32_swap_b32_e32 v18, v20
	v_permlane32_swap_b32_e32 v19, v21
	global_store_dwordx4 v[36:37], v[18:21], off offset:1600
	v_permlane32_swap_b32_e32 v26, v28
	v_permlane32_swap_b32_e32 v27, v29
	global_store_dwordx4 v[36:37], v[26:29], off offset:1632
	s_add_i32 s33, s33, s44
	s_cmpk_lt_i32 s33, 0x200
	s_cbranch_scc0 .LBB0_81
